# p2_glu2: conv GLU staging loop software-pipelined two iterations deep (chunk c+1 loads in flight while chunk c is computed), on top of v8
# baseline (speedup 1.0000x reference)
; #define LAS __attribute__((address_space(3)))
; __device__ __forceinline__ float bflo(unsigned w) { return __uint_as_float(w << 16); }
; __device__ __forceinline__ float bfhi(unsigned w) { return __uint_as_float(w & 0xffff0000u); }
; __device__ __forceinline__ void conv_unit(LAS unsigned char* lds, int u, const bf16* PROJ, const float* conv_w, const float* conv_b, const float* ln_w, const float* ln_b, bf16* MIX, int tid, const WsRef& wsr) {
;     ...
;     for (int it = tid; it < 62 * 64; it += 512) { const int r = it >> 6, cc = it & 63; const int t = t0 - 15 + r;
;         f32x4 u0 = (f32x4){0.f, 0.f, 0.f, 0.f}, u1 = u0;
;         if (t >= 0 && t < SEQ) { const bf16* pr = PROJ + (rowb + t) * INC + 2048 + cc * 8; const u32x4 a = *(const u32x4*)pr, g = *(const u32x4*)(pr + 512);
; #pragma unroll
;             for (int e = 0; e < 4; ++e) { const float a0 = bflo(a[e]), a1 = bfhi(a[e]), g0 = bflo(g[e]), g1 = bfhi(g[e]);
;                 const float v0 = a0 * __builtin_amdgcn_rcpf(1.f + __expf(-g0)), v1 = a1 * __builtin_amdgcn_rcpf(1.f + __expf(-g1));
;                 if (e < 2) { u0[2 * e] = v0; u0[2 * e + 1] = v1; } else { u1[2 * e - 4] = v0; u1[2 * e - 3] = v1; } } }
;         *(LAS f32x4*)(U + r * 512 + cc * 8) = u0; *(LAS f32x4*)(U + r * 512 + cc * 8 + 4) = u1; }
.Lcp_full:
	v_mov_b32_e32 v104, v84
	s_mov_b64 s[10:11], exec
	v_cmp_gt_u32_e32 vcc, s24, v104
	s_and_b64 s[14:15], s[10:11], vcc
	s_mov_b64 exec, s[14:15]
	v_or_b32_e32 v2, s8, v104
	v_mov_b64_e32 v[0:1], s[6:7]
	v_mad_u64_u32 v[0:1], s[30:31], v2, s25, v[0:1]
	v_mad_i32_i24 v1, s9, v218, v1
	v_lshl_add_u64 v[4:5], v[0:1], 0, v[8:9]
	v_lshl_add_u64 v[0:1], v[4:5], 0, s[4:5]
	v_add_co_u32_e32 v4, vcc, 0x1000, v4
	global_load_dwordx4 v[150:153], v[0:1], off offset:1024
	s_nop 0
	v_addc_co_u32_e32 v5, vcc, 0, v5, vcc
	global_load_dwordx4 v[154:157], v[4:5], off
	s_mov_b64 exec, -1
	v_add_u32_e32 v104, 8, v84
	v_add_u32_e32 v106, 0x200, v88
	v_cmp_lt_u32_e32 vcc, s26, v106
	s_andn2_b64 s[10:11], exec, vcc
	v_cmp_gt_u32_e32 vcc, s24, v104
	s_and_b64 s[14:15], s[10:11], vcc
	s_mov_b64 exec, s[14:15]
	v_or_b32_e32 v2, s8, v104
	v_mov_b64_e32 v[0:1], s[6:7]
	v_mad_u64_u32 v[0:1], s[30:31], v2, s25, v[0:1]
	v_mad_i32_i24 v1, s9, v218, v1
	v_lshl_add_u64 v[4:5], v[0:1], 0, v[8:9]
	v_lshl_add_u64 v[0:1], v[4:5], 0, s[4:5]
	v_add_co_u32_e32 v4, vcc, 0x1000, v4
	global_load_dwordx4 v[158:161], v[0:1], off offset:1024
	s_nop 0
	v_addc_co_u32_e32 v5, vcc, 0, v5, vcc
	global_load_dwordx4 v[162:165], v[4:5], off
	s_mov_b64 exec, -1
	s_waitcnt vmcnt(0)
	v_add_u32_e32 v104, 16, v84
	v_add_u32_e32 v106, 0x400, v88
	v_cmp_lt_u32_e32 vcc, s26, v106
	s_andn2_b64 s[10:11], exec, vcc
	v_cmp_gt_u32_e32 vcc, s24, v104
	s_and_b64 s[14:15], s[10:11], vcc
	s_mov_b64 exec, s[14:15]
	v_or_b32_e32 v2, s8, v104
	v_mov_b64_e32 v[0:1], s[6:7]
	v_mad_u64_u32 v[0:1], s[30:31], v2, s25, v[0:1]
	v_mad_i32_i24 v1, s9, v218, v1
	v_lshl_add_u64 v[4:5], v[0:1], 0, v[8:9]
	v_lshl_add_u64 v[0:1], v[4:5], 0, s[4:5]
	v_add_co_u32_e32 v4, vcc, 0x1000, v4
	global_load_dwordx4 v[166:169], v[0:1], off offset:1024
	s_nop 0
	v_addc_co_u32_e32 v5, vcc, 0, v5, vcc
	global_load_dwordx4 v[170:173], v[4:5], off
	s_mov_b64 exec, -1
	v_add_u32_e32 v104, 24, v84
	v_add_u32_e32 v106, 0x600, v88
	v_cmp_lt_u32_e32 vcc, s26, v106
	s_andn2_b64 s[10:11], exec, vcc
	v_cmp_gt_u32_e32 vcc, s24, v104
	s_and_b64 s[14:15], s[10:11], vcc
	s_mov_b64 exec, s[14:15]
	v_or_b32_e32 v2, s8, v104
	v_mov_b64_e32 v[0:1], s[6:7]
	v_mad_u64_u32 v[0:1], s[30:31], v2, s25, v[0:1]
	v_mad_i32_i24 v1, s9, v218, v1
	v_lshl_add_u64 v[4:5], v[0:1], 0, v[8:9]
	v_lshl_add_u64 v[0:1], v[4:5], 0, s[4:5]
	v_add_co_u32_e32 v4, vcc, 0x1000, v4
	global_load_dwordx4 v[174:177], v[0:1], off offset:1024
	s_nop 0
	v_addc_co_u32_e32 v5, vcc, 0, v5, vcc
	global_load_dwordx4 v[178:181], v[4:5], off
	s_mov_b64 exec, -1
	v_mov_b32_e32 v104, v84
	s_mov_b64 s[10:11], exec
	v_cmp_gt_u32_e32 vcc, s24, v104
	s_and_b64 s[14:15], s[10:11], vcc
	v_mov_b32_e32 v0, 0
	v_mov_b32_e32 v1, 0
	v_mov_b32_e32 v2, 0
	v_mov_b32_e32 v3, 0
	v_mov_b32_e32 v4, 0
	v_mov_b32_e32 v5, 0
	v_mov_b32_e32 v6, 0
	v_mov_b32_e32 v7, 0
	s_mov_b64 exec, s[14:15]
	v_mov_b32_e32 v0, v150
	v_mov_b32_e32 v1, v151
	v_mov_b32_e32 v2, v152
	v_mov_b32_e32 v3, v153
	v_mov_b32_e32 v4, v154
	v_mov_b32_e32 v5, v155
	v_mov_b32_e32 v6, v156
	v_mov_b32_e32 v7, v157
	v_and_b32_e32 v90, 0xffff0000, v0
	v_lshlrev_b32_e32 v92, 16, v0
	v_lshlrev_b32_e32 v94, 16, v1
	v_lshlrev_b32_e32 v142, 16, v4
	v_and_b32_e32 v143, 0xffff0000, v4
	v_and_b32_e32 v4, 0xffff0000, v1
	v_lshlrev_b32_e32 v0, 16, v5
	v_and_b32_e32 v1, 0xffff0000, v5
	v_and_b32_e32 v5, 0xffff0000, v2
	v_lshlrev_b32_e32 v96, 16, v2
	v_lshlrev_b32_e32 v144, 16, v6
	v_and_b32_e32 v145, 0xffff0000, v6
	v_lshlrev_b32_e32 v6, 16, v3
	v_and_b32_e32 v98, 0xffff0000, v3
	v_lshlrev_b32_e32 v2, 16, v7
	v_and_b32_e32 v3, 0xffff0000, v7
	v_mul_f32_e32 v7, 0xbfb8aa3b, v90
	v_mul_f32_e32 v90, 0xbfb8aa3b, v92
	v_mul_f32_e32 v4, 0xbfb8aa3b, v4
	v_mul_f32_e32 v92, 0xbfb8aa3b, v94
	v_mul_f32_e32 v5, 0xbfb8aa3b, v5
	v_mul_f32_e32 v94, 0xbfb8aa3b, v96
	v_mul_f32_e32 v6, 0xbfb8aa3b, v6
	v_mul_f32_e32 v96, 0xbfb8aa3b, v98
	v_exp_f32_e32 v7, v7
	v_exp_f32_e32 v90, v90
	v_exp_f32_e32 v4, v4
	v_exp_f32_e32 v92, v92
	v_exp_f32_e32 v5, v5
	v_exp_f32_e32 v94, v94
	v_exp_f32_e32 v6, v6
	v_exp_f32_e32 v96, v96
	v_add_f32_e32 v7, 1.0, v7
	v_add_f32_e32 v90, 1.0, v90
	v_add_f32_e32 v98, 1.0, v4
	v_add_f32_e32 v92, 1.0, v92
	v_add_f32_e32 v100, 1.0, v5
	v_add_f32_e32 v94, 1.0, v94
	v_add_f32_e32 v102, 1.0, v6
	v_add_f32_e32 v96, 1.0, v96
	v_rcp_f32_e32 v5, v7
	v_rcp_f32_e32 v4, v90
	v_rcp_f32_e32 v7, v98
	v_rcp_f32_e32 v6, v92
	v_rcp_f32_e32 v147, v100
	v_rcp_f32_e32 v146, v94
	v_rcp_f32_e32 v148, v102
	v_rcp_f32_e32 v149, v96
	v_pk_mul_f32 v[4:5], v[4:5], v[142:143]
	v_pk_mul_f32 v[6:7], v[6:7], v[0:1]
	v_pk_mul_f32 v[0:1], v[146:147], v[144:145]
	v_pk_mul_f32 v[2:3], v[148:149], v[2:3]
	s_mov_b64 exec, s[10:11]
	v_mov_b32_e32 v108, v86
	ds_write_b128 v108, v[4:7]
	ds_write_b128 v108, v[0:3] offset:16
	s_mov_b64 exec, -1
	v_add_u32_e32 v104, 8, v84
	v_add_u32_e32 v106, 0x200, v88
	v_cmp_lt_u32_e32 vcc, s26, v106
	s_andn2_b64 s[10:11], exec, vcc
	v_cmp_gt_u32_e32 vcc, s24, v104
	s_and_b64 s[14:15], s[10:11], vcc
	v_mov_b32_e32 v0, 0
	v_mov_b32_e32 v1, 0
	v_mov_b32_e32 v2, 0
	v_mov_b32_e32 v3, 0
	v_mov_b32_e32 v4, 0
	v_mov_b32_e32 v5, 0
	v_mov_b32_e32 v6, 0
	v_mov_b32_e32 v7, 0
	s_mov_b64 exec, s[14:15]
	v_mov_b32_e32 v0, v158
	v_mov_b32_e32 v1, v159
	v_mov_b32_e32 v2, v160
	v_mov_b32_e32 v3, v161
	v_mov_b32_e32 v4, v162
	v_mov_b32_e32 v5, v163
	v_mov_b32_e32 v6, v164
	v_mov_b32_e32 v7, v165
	v_and_b32_e32 v90, 0xffff0000, v0
	v_lshlrev_b32_e32 v92, 16, v0
	v_lshlrev_b32_e32 v94, 16, v1
	v_lshlrev_b32_e32 v142, 16, v4
	v_and_b32_e32 v143, 0xffff0000, v4
	v_and_b32_e32 v4, 0xffff0000, v1
	v_lshlrev_b32_e32 v0, 16, v5
	v_and_b32_e32 v1, 0xffff0000, v5
	v_and_b32_e32 v5, 0xffff0000, v2
; #define LAS __attribute__((address_space(3)))
; __device__ __forceinline__ float bflo(unsigned w) { return __uint_as_float(w << 16); }
; __device__ __forceinline__ float bfhi(unsigned w) { return __uint_as_float(w & 0xffff0000u); }
; __device__ __forceinline__ void conv_unit(LAS unsigned char* lds, int u, const bf16* PROJ, const float* conv_w, const float* conv_b, const float* ln_w, const float* ln_b, bf16* MIX, int tid, const WsRef& wsr) {
;     ...
;     for (int it = tid; it < 62 * 64; it += 512) { const int r = it >> 6, cc = it & 63; const int t = t0 - 15 + r;
;         f32x4 u0 = (f32x4){0.f, 0.f, 0.f, 0.f}, u1 = u0;
;         if (t >= 0 && t < SEQ) { const bf16* pr = PROJ + (rowb + t) * INC + 2048 + cc * 8; const u32x4 a = *(const u32x4*)pr, g = *(const u32x4*)(pr + 512);
; #pragma unroll
;             for (int e = 0; e < 4; ++e) { const float a0 = bflo(a[e]), a1 = bfhi(a[e]), g0 = bflo(g[e]), g1 = bfhi(g[e]);
;                 const float v0 = a0 * __builtin_amdgcn_rcpf(1.f + __expf(-g0)), v1 = a1 * __builtin_amdgcn_rcpf(1.f + __expf(-g1));
;                 if (e < 2) { u0[2 * e] = v0; u0[2 * e + 1] = v1; } else { u1[2 * e - 4] = v0; u1[2 * e - 3] = v1; } } }
;         *(LAS f32x4*)(U + r * 512 + cc * 8) = u0; *(LAS f32x4*)(U + r * 512 + cc * 8 + 4) = u1; }
	v_lshlrev_b32_e32 v96, 16, v2
	v_lshlrev_b32_e32 v144, 16, v6
	v_and_b32_e32 v145, 0xffff0000, v6
	v_lshlrev_b32_e32 v6, 16, v3
	v_and_b32_e32 v98, 0xffff0000, v3
	v_lshlrev_b32_e32 v2, 16, v7
	v_and_b32_e32 v3, 0xffff0000, v7
	v_mul_f32_e32 v7, 0xbfb8aa3b, v90
	v_mul_f32_e32 v90, 0xbfb8aa3b, v92
	v_mul_f32_e32 v4, 0xbfb8aa3b, v4
	v_mul_f32_e32 v92, 0xbfb8aa3b, v94
	v_mul_f32_e32 v5, 0xbfb8aa3b, v5
	v_mul_f32_e32 v94, 0xbfb8aa3b, v96
	v_mul_f32_e32 v6, 0xbfb8aa3b, v6
	v_mul_f32_e32 v96, 0xbfb8aa3b, v98
	v_exp_f32_e32 v7, v7
	v_exp_f32_e32 v90, v90
	v_exp_f32_e32 v4, v4
	v_exp_f32_e32 v92, v92
	v_exp_f32_e32 v5, v5
	v_exp_f32_e32 v94, v94
	v_exp_f32_e32 v6, v6
	v_exp_f32_e32 v96, v96
	v_add_f32_e32 v7, 1.0, v7
	v_add_f32_e32 v90, 1.0, v90
	v_add_f32_e32 v98, 1.0, v4
	v_add_f32_e32 v92, 1.0, v92
	v_add_f32_e32 v100, 1.0, v5
	v_add_f32_e32 v94, 1.0, v94
	v_add_f32_e32 v102, 1.0, v6
	v_add_f32_e32 v96, 1.0, v96
	v_rcp_f32_e32 v5, v7
	v_rcp_f32_e32 v4, v90
	v_rcp_f32_e32 v7, v98
	v_rcp_f32_e32 v6, v92
	v_rcp_f32_e32 v147, v100
	v_rcp_f32_e32 v146, v94
	v_rcp_f32_e32 v148, v102
	v_rcp_f32_e32 v149, v96
	v_pk_mul_f32 v[4:5], v[4:5], v[142:143]
	v_pk_mul_f32 v[6:7], v[6:7], v[0:1]
	v_pk_mul_f32 v[0:1], v[146:147], v[144:145]
	v_pk_mul_f32 v[2:3], v[148:149], v[2:3]
	s_mov_b64 exec, s[10:11]
	v_add_u32_e32 v108, 0x4000, v86
	ds_write_b128 v108, v[4:7]
	ds_write_b128 v108, v[0:3] offset:16
	s_mov_b64 exec, -1
	s_waitcnt vmcnt(0)
	v_add_u32_e32 v104, 32, v84
	v_add_u32_e32 v106, 0x800, v88
	v_cmp_lt_u32_e32 vcc, s26, v106
	s_andn2_b64 s[10:11], exec, vcc
	v_cmp_gt_u32_e32 vcc, s24, v104
	s_and_b64 s[14:15], s[10:11], vcc
	s_mov_b64 exec, s[14:15]
	v_or_b32_e32 v2, s8, v104
	v_mov_b64_e32 v[0:1], s[6:7]
	v_mad_u64_u32 v[0:1], s[30:31], v2, s25, v[0:1]
	v_mad_i32_i24 v1, s9, v218, v1
	v_lshl_add_u64 v[4:5], v[0:1], 0, v[8:9]
	v_lshl_add_u64 v[0:1], v[4:5], 0, s[4:5]
	v_add_co_u32_e32 v4, vcc, 0x1000, v4
	global_load_dwordx4 v[150:153], v[0:1], off offset:1024
	s_nop 0
	v_addc_co_u32_e32 v5, vcc, 0, v5, vcc
	global_load_dwordx4 v[154:157], v[4:5], off
	s_mov_b64 exec, -1
	v_add_u32_e32 v104, 40, v84
	v_add_u32_e32 v106, 0xa00, v88
	v_cmp_lt_u32_e32 vcc, s26, v106
	s_andn2_b64 s[10:11], exec, vcc
	v_cmp_gt_u32_e32 vcc, s24, v104
	s_and_b64 s[14:15], s[10:11], vcc
	s_mov_b64 exec, s[14:15]
	v_or_b32_e32 v2, s8, v104
	v_mov_b64_e32 v[0:1], s[6:7]
	v_mad_u64_u32 v[0:1], s[30:31], v2, s25, v[0:1]
	v_mad_i32_i24 v1, s9, v218, v1
	v_lshl_add_u64 v[4:5], v[0:1], 0, v[8:9]
	v_lshl_add_u64 v[0:1], v[4:5], 0, s[4:5]
	v_add_co_u32_e32 v4, vcc, 0x1000, v4
	global_load_dwordx4 v[158:161], v[0:1], off offset:1024
	s_nop 0
	v_addc_co_u32_e32 v5, vcc, 0, v5, vcc
	global_load_dwordx4 v[162:165], v[4:5], off
	s_mov_b64 exec, -1
	v_add_u32_e32 v104, 16, v84
	v_add_u32_e32 v106, 0x400, v88
	v_cmp_lt_u32_e32 vcc, s26, v106
	s_andn2_b64 s[10:11], exec, vcc
	v_cmp_gt_u32_e32 vcc, s24, v104
	s_and_b64 s[14:15], s[10:11], vcc
	v_mov_b32_e32 v0, 0
	v_mov_b32_e32 v1, 0
	v_mov_b32_e32 v2, 0
	v_mov_b32_e32 v3, 0
	v_mov_b32_e32 v4, 0
	v_mov_b32_e32 v5, 0
	v_mov_b32_e32 v6, 0
	v_mov_b32_e32 v7, 0
	s_mov_b64 exec, s[14:15]
	v_mov_b32_e32 v0, v166
	v_mov_b32_e32 v1, v167
	v_mov_b32_e32 v2, v168
	v_mov_b32_e32 v3, v169
	v_mov_b32_e32 v4, v170
	v_mov_b32_e32 v5, v171
	v_mov_b32_e32 v6, v172
	v_mov_b32_e32 v7, v173
	v_and_b32_e32 v90, 0xffff0000, v0
	v_lshlrev_b32_e32 v92, 16, v0
	v_lshlrev_b32_e32 v94, 16, v1
	v_lshlrev_b32_e32 v142, 16, v4
	v_and_b32_e32 v143, 0xffff0000, v4
	v_and_b32_e32 v4, 0xffff0000, v1
	v_lshlrev_b32_e32 v0, 16, v5
	v_and_b32_e32 v1, 0xffff0000, v5
	v_and_b32_e32 v5, 0xffff0000, v2
	v_lshlrev_b32_e32 v96, 16, v2
	v_lshlrev_b32_e32 v144, 16, v6
	v_and_b32_e32 v145, 0xffff0000, v6
	v_lshlrev_b32_e32 v6, 16, v3
	v_and_b32_e32 v98, 0xffff0000, v3
	v_lshlrev_b32_e32 v2, 16, v7
	v_and_b32_e32 v3, 0xffff0000, v7
	v_mul_f32_e32 v7, 0xbfb8aa3b, v90
	v_mul_f32_e32 v90, 0xbfb8aa3b, v92
	v_mul_f32_e32 v4, 0xbfb8aa3b, v4
	v_mul_f32_e32 v92, 0xbfb8aa3b, v94
	v_mul_f32_e32 v5, 0xbfb8aa3b, v5
	v_mul_f32_e32 v94, 0xbfb8aa3b, v96
	v_mul_f32_e32 v6, 0xbfb8aa3b, v6
	v_mul_f32_e32 v96, 0xbfb8aa3b, v98
	v_exp_f32_e32 v7, v7
	v_exp_f32_e32 v90, v90
	v_exp_f32_e32 v4, v4
	v_exp_f32_e32 v92, v92
	v_exp_f32_e32 v5, v5
	v_exp_f32_e32 v94, v94
	v_exp_f32_e32 v6, v6
	v_exp_f32_e32 v96, v96
	v_add_f32_e32 v7, 1.0, v7
	v_add_f32_e32 v90, 1.0, v90
	v_add_f32_e32 v98, 1.0, v4
	v_add_f32_e32 v92, 1.0, v92
	v_add_f32_e32 v100, 1.0, v5
	v_add_f32_e32 v94, 1.0, v94
	v_add_f32_e32 v102, 1.0, v6
	v_add_f32_e32 v96, 1.0, v96
	v_rcp_f32_e32 v5, v7
	v_rcp_f32_e32 v4, v90
	v_rcp_f32_e32 v7, v98
	v_rcp_f32_e32 v6, v92
	v_rcp_f32_e32 v147, v100
	v_rcp_f32_e32 v146, v94
	v_rcp_f32_e32 v148, v102
	v_rcp_f32_e32 v149, v96
	v_pk_mul_f32 v[4:5], v[4:5], v[142:143]
	v_pk_mul_f32 v[6:7], v[6:7], v[0:1]
	v_pk_mul_f32 v[0:1], v[146:147], v[144:145]
	v_pk_mul_f32 v[2:3], v[148:149], v[2:3]
	s_mov_b64 exec, s[10:11]
	v_add_u32_e32 v108, 0x8000, v86
	ds_write_b128 v108, v[4:7]
	ds_write_b128 v108, v[0:3] offset:16
	s_mov_b64 exec, -1
	v_add_u32_e32 v104, 24, v84
	v_add_u32_e32 v106, 0x600, v88
	v_cmp_lt_u32_e32 vcc, s26, v106
	s_andn2_b64 s[10:11], exec, vcc
	v_cmp_gt_u32_e32 vcc, s24, v104
	s_and_b64 s[14:15], s[10:11], vcc
	v_mov_b32_e32 v0, 0
	v_mov_b32_e32 v1, 0
	v_mov_b32_e32 v2, 0
	v_mov_b32_e32 v3, 0
	v_mov_b32_e32 v4, 0
	v_mov_b32_e32 v5, 0
	v_mov_b32_e32 v6, 0
	v_mov_b32_e32 v7, 0
	s_mov_b64 exec, s[14:15]
	v_mov_b32_e32 v0, v174
	v_mov_b32_e32 v1, v175
	v_mov_b32_e32 v2, v176
	v_mov_b32_e32 v3, v177
	v_mov_b32_e32 v4, v178
	v_mov_b32_e32 v5, v179
	v_mov_b32_e32 v6, v180
	v_mov_b32_e32 v7, v181
; #define LAS __attribute__((address_space(3)))
; __device__ __forceinline__ float bflo(unsigned w) { return __uint_as_float(w << 16); }
; __device__ __forceinline__ float bfhi(unsigned w) { return __uint_as_float(w & 0xffff0000u); }
; __device__ __forceinline__ void conv_unit(LAS unsigned char* lds, int u, const bf16* PROJ, const float* conv_w, const float* conv_b, const float* ln_w, const float* ln_b, bf16* MIX, int tid, const WsRef& wsr) {
;     ...
;     for (int it = tid; it < 62 * 64; it += 512) { const int r = it >> 6, cc = it & 63; const int t = t0 - 15 + r;
;         f32x4 u0 = (f32x4){0.f, 0.f, 0.f, 0.f}, u1 = u0;
;         if (t >= 0 && t < SEQ) { const bf16* pr = PROJ + (rowb + t) * INC + 2048 + cc * 8; const u32x4 a = *(const u32x4*)pr, g = *(const u32x4*)(pr + 512);
; #pragma unroll
;             for (int e = 0; e < 4; ++e) { const float a0 = bflo(a[e]), a1 = bfhi(a[e]), g0 = bflo(g[e]), g1 = bfhi(g[e]);
;                 const float v0 = a0 * __builtin_amdgcn_rcpf(1.f + __expf(-g0)), v1 = a1 * __builtin_amdgcn_rcpf(1.f + __expf(-g1));
;                 if (e < 2) { u0[2 * e] = v0; u0[2 * e + 1] = v1; } else { u1[2 * e - 4] = v0; u1[2 * e - 3] = v1; } } }
;         *(LAS f32x4*)(U + r * 512 + cc * 8) = u0; *(LAS f32x4*)(U + r * 512 + cc * 8 + 4) = u1; }
	v_and_b32_e32 v90, 0xffff0000, v0
	v_lshlrev_b32_e32 v92, 16, v0
	v_lshlrev_b32_e32 v94, 16, v1
	v_lshlrev_b32_e32 v142, 16, v4
	v_and_b32_e32 v143, 0xffff0000, v4
	v_and_b32_e32 v4, 0xffff0000, v1
	v_lshlrev_b32_e32 v0, 16, v5
	v_and_b32_e32 v1, 0xffff0000, v5
	v_and_b32_e32 v5, 0xffff0000, v2
	v_lshlrev_b32_e32 v96, 16, v2
	v_lshlrev_b32_e32 v144, 16, v6
	v_and_b32_e32 v145, 0xffff0000, v6
	v_lshlrev_b32_e32 v6, 16, v3
	v_and_b32_e32 v98, 0xffff0000, v3
	v_lshlrev_b32_e32 v2, 16, v7
	v_and_b32_e32 v3, 0xffff0000, v7
	v_mul_f32_e32 v7, 0xbfb8aa3b, v90
	v_mul_f32_e32 v90, 0xbfb8aa3b, v92
	v_mul_f32_e32 v4, 0xbfb8aa3b, v4
	v_mul_f32_e32 v92, 0xbfb8aa3b, v94
	v_mul_f32_e32 v5, 0xbfb8aa3b, v5
	v_mul_f32_e32 v94, 0xbfb8aa3b, v96
	v_mul_f32_e32 v6, 0xbfb8aa3b, v6
	v_mul_f32_e32 v96, 0xbfb8aa3b, v98
	v_exp_f32_e32 v7, v7
	v_exp_f32_e32 v90, v90
	v_exp_f32_e32 v4, v4
	v_exp_f32_e32 v92, v92
	v_exp_f32_e32 v5, v5
	v_exp_f32_e32 v94, v94
	v_exp_f32_e32 v6, v6
	v_exp_f32_e32 v96, v96
	v_add_f32_e32 v7, 1.0, v7
	v_add_f32_e32 v90, 1.0, v90
	v_add_f32_e32 v98, 1.0, v4
	v_add_f32_e32 v92, 1.0, v92
	v_add_f32_e32 v100, 1.0, v5
	v_add_f32_e32 v94, 1.0, v94
	v_add_f32_e32 v102, 1.0, v6
	v_add_f32_e32 v96, 1.0, v96
	v_rcp_f32_e32 v5, v7
	v_rcp_f32_e32 v4, v90
	v_rcp_f32_e32 v7, v98
	v_rcp_f32_e32 v6, v92
	v_rcp_f32_e32 v147, v100
	v_rcp_f32_e32 v146, v94
	v_rcp_f32_e32 v148, v102
	v_rcp_f32_e32 v149, v96
	v_pk_mul_f32 v[4:5], v[4:5], v[142:143]
	v_pk_mul_f32 v[6:7], v[6:7], v[0:1]
	v_pk_mul_f32 v[0:1], v[146:147], v[144:145]
	v_pk_mul_f32 v[2:3], v[148:149], v[2:3]
	s_mov_b64 exec, s[10:11]
	v_add_u32_e32 v108, 0xc000, v86
	ds_write_b128 v108, v[4:7]
	ds_write_b128 v108, v[0:3] offset:16
	s_mov_b64 exec, -1
	s_waitcnt vmcnt(0)
	v_add_u32_e32 v104, 48, v84
	v_add_u32_e32 v106, 0xc00, v88
	v_cmp_lt_u32_e32 vcc, s26, v106
	s_andn2_b64 s[10:11], exec, vcc
	v_cmp_gt_u32_e32 vcc, s24, v104
	s_and_b64 s[14:15], s[10:11], vcc
	s_mov_b64 exec, s[14:15]
	v_or_b32_e32 v2, s8, v104
	v_mov_b64_e32 v[0:1], s[6:7]
	v_mad_u64_u32 v[0:1], s[30:31], v2, s25, v[0:1]
	v_mad_i32_i24 v1, s9, v218, v1
	v_lshl_add_u64 v[4:5], v[0:1], 0, v[8:9]
	v_lshl_add_u64 v[0:1], v[4:5], 0, s[4:5]
	v_add_co_u32_e32 v4, vcc, 0x1000, v4
	global_load_dwordx4 v[166:169], v[0:1], off offset:1024
	s_nop 0
	v_addc_co_u32_e32 v5, vcc, 0, v5, vcc
	global_load_dwordx4 v[170:173], v[4:5], off
	s_mov_b64 exec, -1
	v_add_u32_e32 v104, 56, v84
	v_add_u32_e32 v106, 0xe00, v88
	v_cmp_lt_u32_e32 vcc, s26, v106
	s_andn2_b64 s[10:11], exec, vcc
	v_cmp_gt_u32_e32 vcc, s24, v104
	s_and_b64 s[14:15], s[10:11], vcc
	s_mov_b64 exec, s[14:15]
	v_or_b32_e32 v2, s8, v104
	v_mov_b64_e32 v[0:1], s[6:7]
	v_mad_u64_u32 v[0:1], s[30:31], v2, s25, v[0:1]
	v_mad_i32_i24 v1, s9, v218, v1
	v_lshl_add_u64 v[4:5], v[0:1], 0, v[8:9]
	v_lshl_add_u64 v[0:1], v[4:5], 0, s[4:5]
	v_add_co_u32_e32 v4, vcc, 0x1000, v4
	global_load_dwordx4 v[174:177], v[0:1], off offset:1024
	s_nop 0
	v_addc_co_u32_e32 v5, vcc, 0, v5, vcc
	global_load_dwordx4 v[178:181], v[4:5], off
	s_mov_b64 exec, -1
	v_add_u32_e32 v104, 32, v84
	v_add_u32_e32 v106, 0x800, v88
	v_cmp_lt_u32_e32 vcc, s26, v106
	s_andn2_b64 s[10:11], exec, vcc
	v_cmp_gt_u32_e32 vcc, s24, v104
	s_and_b64 s[14:15], s[10:11], vcc
	v_mov_b32_e32 v0, 0
	v_mov_b32_e32 v1, 0
	v_mov_b32_e32 v2, 0
	v_mov_b32_e32 v3, 0
	v_mov_b32_e32 v4, 0
	v_mov_b32_e32 v5, 0
	v_mov_b32_e32 v6, 0
	v_mov_b32_e32 v7, 0
	s_mov_b64 exec, s[14:15]
	v_mov_b32_e32 v0, v150
	v_mov_b32_e32 v1, v151
	v_mov_b32_e32 v2, v152
	v_mov_b32_e32 v3, v153
	v_mov_b32_e32 v4, v154
	v_mov_b32_e32 v5, v155
	v_mov_b32_e32 v6, v156
	v_mov_b32_e32 v7, v157
	v_and_b32_e32 v90, 0xffff0000, v0
	v_lshlrev_b32_e32 v92, 16, v0
	v_lshlrev_b32_e32 v94, 16, v1
	v_lshlrev_b32_e32 v142, 16, v4
	v_and_b32_e32 v143, 0xffff0000, v4
	v_and_b32_e32 v4, 0xffff0000, v1
	v_lshlrev_b32_e32 v0, 16, v5
	v_and_b32_e32 v1, 0xffff0000, v5
	v_and_b32_e32 v5, 0xffff0000, v2
	v_lshlrev_b32_e32 v96, 16, v2
	v_lshlrev_b32_e32 v144, 16, v6
	v_and_b32_e32 v145, 0xffff0000, v6
	v_lshlrev_b32_e32 v6, 16, v3
	v_and_b32_e32 v98, 0xffff0000, v3
	v_lshlrev_b32_e32 v2, 16, v7
	v_and_b32_e32 v3, 0xffff0000, v7
	v_mul_f32_e32 v7, 0xbfb8aa3b, v90
	v_mul_f32_e32 v90, 0xbfb8aa3b, v92
	v_mul_f32_e32 v4, 0xbfb8aa3b, v4
	v_mul_f32_e32 v92, 0xbfb8aa3b, v94
	v_mul_f32_e32 v5, 0xbfb8aa3b, v5
	v_mul_f32_e32 v94, 0xbfb8aa3b, v96
	v_mul_f32_e32 v6, 0xbfb8aa3b, v6
	v_mul_f32_e32 v96, 0xbfb8aa3b, v98
	v_exp_f32_e32 v7, v7
	v_exp_f32_e32 v90, v90
	v_exp_f32_e32 v4, v4
	v_exp_f32_e32 v92, v92
	v_exp_f32_e32 v5, v5
	v_exp_f32_e32 v94, v94
	v_exp_f32_e32 v6, v6
	v_exp_f32_e32 v96, v96
	v_add_f32_e32 v7, 1.0, v7
	v_add_f32_e32 v90, 1.0, v90
	v_add_f32_e32 v98, 1.0, v4
	v_add_f32_e32 v92, 1.0, v92
	v_add_f32_e32 v100, 1.0, v5
	v_add_f32_e32 v94, 1.0, v94
	v_add_f32_e32 v102, 1.0, v6
	v_add_f32_e32 v96, 1.0, v96
	v_rcp_f32_e32 v5, v7
	v_rcp_f32_e32 v4, v90
	v_rcp_f32_e32 v7, v98
	v_rcp_f32_e32 v6, v92
	v_rcp_f32_e32 v147, v100
	v_rcp_f32_e32 v146, v94
	v_rcp_f32_e32 v148, v102
	v_rcp_f32_e32 v149, v96
	v_pk_mul_f32 v[4:5], v[4:5], v[142:143]
	v_pk_mul_f32 v[6:7], v[6:7], v[0:1]
	v_pk_mul_f32 v[0:1], v[146:147], v[144:145]
	v_pk_mul_f32 v[2:3], v[148:149], v[2:3]
	s_mov_b64 exec, s[10:11]
	v_add_u32_e32 v108, 0x10000, v86
	ds_write_b128 v108, v[4:7]
	ds_write_b128 v108, v[0:3] offset:16
	s_mov_b64 exec, -1
	v_add_u32_e32 v104, 40, v84
	v_add_u32_e32 v106, 0xa00, v88
	v_cmp_lt_u32_e32 vcc, s26, v106
	s_andn2_b64 s[10:11], exec, vcc
	v_cmp_gt_u32_e32 vcc, s24, v104
	s_and_b64 s[14:15], s[10:11], vcc
	v_mov_b32_e32 v0, 0
	v_mov_b32_e32 v1, 0
	v_mov_b32_e32 v2, 0
	v_mov_b32_e32 v3, 0
	v_mov_b32_e32 v4, 0
; #define LAS __attribute__((address_space(3)))
; __device__ __forceinline__ float bflo(unsigned w) { return __uint_as_float(w << 16); }
; __device__ __forceinline__ float bfhi(unsigned w) { return __uint_as_float(w & 0xffff0000u); }
; __device__ __forceinline__ void conv_unit(LAS unsigned char* lds, int u, const bf16* PROJ, const float* conv_w, const float* conv_b, const float* ln_w, const float* ln_b, bf16* MIX, int tid, const WsRef& wsr) {
;     ...
;     for (int it = tid; it < 62 * 64; it += 512) { const int r = it >> 6, cc = it & 63; const int t = t0 - 15 + r;
;         f32x4 u0 = (f32x4){0.f, 0.f, 0.f, 0.f}, u1 = u0;
;         if (t >= 0 && t < SEQ) { const bf16* pr = PROJ + (rowb + t) * INC + 2048 + cc * 8; const u32x4 a = *(const u32x4*)pr, g = *(const u32x4*)(pr + 512);
; #pragma unroll
;             for (int e = 0; e < 4; ++e) { const float a0 = bflo(a[e]), a1 = bfhi(a[e]), g0 = bflo(g[e]), g1 = bfhi(g[e]);
;                 const float v0 = a0 * __builtin_amdgcn_rcpf(1.f + __expf(-g0)), v1 = a1 * __builtin_amdgcn_rcpf(1.f + __expf(-g1));
;                 if (e < 2) { u0[2 * e] = v0; u0[2 * e + 1] = v1; } else { u1[2 * e - 4] = v0; u1[2 * e - 3] = v1; } } }
;         *(LAS f32x4*)(U + r * 512 + cc * 8) = u0; *(LAS f32x4*)(U + r * 512 + cc * 8 + 4) = u1; }
	v_mov_b32_e32 v5, 0
	v_mov_b32_e32 v6, 0
	v_mov_b32_e32 v7, 0
	s_mov_b64 exec, s[14:15]
	v_mov_b32_e32 v0, v158
	v_mov_b32_e32 v1, v159
	v_mov_b32_e32 v2, v160
	v_mov_b32_e32 v3, v161
	v_mov_b32_e32 v4, v162
	v_mov_b32_e32 v5, v163
	v_mov_b32_e32 v6, v164
	v_mov_b32_e32 v7, v165
	v_and_b32_e32 v90, 0xffff0000, v0
	v_lshlrev_b32_e32 v92, 16, v0
	v_lshlrev_b32_e32 v94, 16, v1
	v_lshlrev_b32_e32 v142, 16, v4
	v_and_b32_e32 v143, 0xffff0000, v4
	v_and_b32_e32 v4, 0xffff0000, v1
	v_lshlrev_b32_e32 v0, 16, v5
	v_and_b32_e32 v1, 0xffff0000, v5
	v_and_b32_e32 v5, 0xffff0000, v2
	v_lshlrev_b32_e32 v96, 16, v2
	v_lshlrev_b32_e32 v144, 16, v6
	v_and_b32_e32 v145, 0xffff0000, v6
	v_lshlrev_b32_e32 v6, 16, v3
	v_and_b32_e32 v98, 0xffff0000, v3
	v_lshlrev_b32_e32 v2, 16, v7
	v_and_b32_e32 v3, 0xffff0000, v7
	v_mul_f32_e32 v7, 0xbfb8aa3b, v90
	v_mul_f32_e32 v90, 0xbfb8aa3b, v92
	v_mul_f32_e32 v4, 0xbfb8aa3b, v4
	v_mul_f32_e32 v92, 0xbfb8aa3b, v94
	v_mul_f32_e32 v5, 0xbfb8aa3b, v5
	v_mul_f32_e32 v94, 0xbfb8aa3b, v96
	v_mul_f32_e32 v6, 0xbfb8aa3b, v6
	v_mul_f32_e32 v96, 0xbfb8aa3b, v98
	v_exp_f32_e32 v7, v7
	v_exp_f32_e32 v90, v90
	v_exp_f32_e32 v4, v4
	v_exp_f32_e32 v92, v92
	v_exp_f32_e32 v5, v5
	v_exp_f32_e32 v94, v94
	v_exp_f32_e32 v6, v6
	v_exp_f32_e32 v96, v96
	v_add_f32_e32 v7, 1.0, v7
	v_add_f32_e32 v90, 1.0, v90
	v_add_f32_e32 v98, 1.0, v4
	v_add_f32_e32 v92, 1.0, v92
	v_add_f32_e32 v100, 1.0, v5
	v_add_f32_e32 v94, 1.0, v94
	v_add_f32_e32 v102, 1.0, v6
	v_add_f32_e32 v96, 1.0, v96
	v_rcp_f32_e32 v5, v7
	v_rcp_f32_e32 v4, v90
	v_rcp_f32_e32 v7, v98
	v_rcp_f32_e32 v6, v92
	v_rcp_f32_e32 v147, v100
	v_rcp_f32_e32 v146, v94
	v_rcp_f32_e32 v148, v102
	v_rcp_f32_e32 v149, v96
	v_pk_mul_f32 v[4:5], v[4:5], v[142:143]
	v_pk_mul_f32 v[6:7], v[6:7], v[0:1]
	v_pk_mul_f32 v[0:1], v[146:147], v[144:145]
	v_pk_mul_f32 v[2:3], v[148:149], v[2:3]
	s_mov_b64 exec, s[10:11]
	v_add_u32_e32 v108, 0x14000, v86
	ds_write_b128 v108, v[4:7]
	ds_write_b128 v108, v[0:3] offset:16
	s_mov_b64 exec, -1
	s_waitcnt vmcnt(0)
	v_add_u32_e32 v104, 48, v84
	v_add_u32_e32 v106, 0xc00, v88
	v_cmp_lt_u32_e32 vcc, s26, v106
	s_andn2_b64 s[10:11], exec, vcc
	v_cmp_gt_u32_e32 vcc, s24, v104
	s_and_b64 s[14:15], s[10:11], vcc
	v_mov_b32_e32 v0, 0
	v_mov_b32_e32 v1, 0
	v_mov_b32_e32 v2, 0
	v_mov_b32_e32 v3, 0
	v_mov_b32_e32 v4, 0
	v_mov_b32_e32 v5, 0
	v_mov_b32_e32 v6, 0
	v_mov_b32_e32 v7, 0
	s_mov_b64 exec, s[14:15]
	v_mov_b32_e32 v0, v166
	v_mov_b32_e32 v1, v167
	v_mov_b32_e32 v2, v168
	v_mov_b32_e32 v3, v169
	v_mov_b32_e32 v4, v170
	v_mov_b32_e32 v5, v171
	v_mov_b32_e32 v6, v172
	v_mov_b32_e32 v7, v173
	v_and_b32_e32 v90, 0xffff0000, v0
	v_lshlrev_b32_e32 v92, 16, v0
	v_lshlrev_b32_e32 v94, 16, v1
	v_lshlrev_b32_e32 v142, 16, v4
	v_and_b32_e32 v143, 0xffff0000, v4
	v_and_b32_e32 v4, 0xffff0000, v1
	v_lshlrev_b32_e32 v0, 16, v5
	v_and_b32_e32 v1, 0xffff0000, v5
	v_and_b32_e32 v5, 0xffff0000, v2
	v_lshlrev_b32_e32 v96, 16, v2
	v_lshlrev_b32_e32 v144, 16, v6
	v_and_b32_e32 v145, 0xffff0000, v6
	v_lshlrev_b32_e32 v6, 16, v3
	v_and_b32_e32 v98, 0xffff0000, v3
	v_lshlrev_b32_e32 v2, 16, v7
	v_and_b32_e32 v3, 0xffff0000, v7
	v_mul_f32_e32 v7, 0xbfb8aa3b, v90
	v_mul_f32_e32 v90, 0xbfb8aa3b, v92
	v_mul_f32_e32 v4, 0xbfb8aa3b, v4
	v_mul_f32_e32 v92, 0xbfb8aa3b, v94
	v_mul_f32_e32 v5, 0xbfb8aa3b, v5
	v_mul_f32_e32 v94, 0xbfb8aa3b, v96
	v_mul_f32_e32 v6, 0xbfb8aa3b, v6
	v_mul_f32_e32 v96, 0xbfb8aa3b, v98
	v_exp_f32_e32 v7, v7
	v_exp_f32_e32 v90, v90
	v_exp_f32_e32 v4, v4
	v_exp_f32_e32 v92, v92
	v_exp_f32_e32 v5, v5
	v_exp_f32_e32 v94, v94
	v_exp_f32_e32 v6, v6
	v_exp_f32_e32 v96, v96
	v_add_f32_e32 v7, 1.0, v7
	v_add_f32_e32 v90, 1.0, v90
	v_add_f32_e32 v98, 1.0, v4
	v_add_f32_e32 v92, 1.0, v92
	v_add_f32_e32 v100, 1.0, v5
	v_add_f32_e32 v94, 1.0, v94
	v_add_f32_e32 v102, 1.0, v6
	v_add_f32_e32 v96, 1.0, v96
	v_rcp_f32_e32 v5, v7
	v_rcp_f32_e32 v4, v90
	v_rcp_f32_e32 v7, v98
	v_rcp_f32_e32 v6, v92
	v_rcp_f32_e32 v147, v100
	v_rcp_f32_e32 v146, v94
	v_rcp_f32_e32 v148, v102
	v_rcp_f32_e32 v149, v96
	v_pk_mul_f32 v[4:5], v[4:5], v[142:143]
	v_pk_mul_f32 v[6:7], v[6:7], v[0:1]
	v_pk_mul_f32 v[0:1], v[146:147], v[144:145]
	v_pk_mul_f32 v[2:3], v[148:149], v[2:3]
	s_mov_b64 exec, s[10:11]
	v_add_u32_e32 v108, 0x18000, v86
	ds_write_b128 v108, v[4:7]
	ds_write_b128 v108, v[0:3] offset:16
	s_mov_b64 exec, -1
	v_add_u32_e32 v104, 56, v84
	v_add_u32_e32 v106, 0xe00, v88
	v_cmp_lt_u32_e32 vcc, s26, v106
	s_andn2_b64 s[10:11], exec, vcc
	v_cmp_gt_u32_e32 vcc, s24, v104
	s_and_b64 s[14:15], s[10:11], vcc
	v_mov_b32_e32 v0, 0
	v_mov_b32_e32 v1, 0
	v_mov_b32_e32 v2, 0
	v_mov_b32_e32 v3, 0
	v_mov_b32_e32 v4, 0
	v_mov_b32_e32 v5, 0
	v_mov_b32_e32 v6, 0
	v_mov_b32_e32 v7, 0
	s_mov_b64 exec, s[14:15]
	v_mov_b32_e32 v0, v174
	v_mov_b32_e32 v1, v175
	v_mov_b32_e32 v2, v176
	v_mov_b32_e32 v3, v177
	v_mov_b32_e32 v4, v178
	v_mov_b32_e32 v5, v179
	v_mov_b32_e32 v6, v180
	v_mov_b32_e32 v7, v181
	v_and_b32_e32 v90, 0xffff0000, v0
	v_lshlrev_b32_e32 v92, 16, v0
	v_lshlrev_b32_e32 v94, 16, v1
	v_lshlrev_b32_e32 v142, 16, v4
	v_and_b32_e32 v143, 0xffff0000, v4
	v_and_b32_e32 v4, 0xffff0000, v1
	v_lshlrev_b32_e32 v0, 16, v5
	v_and_b32_e32 v1, 0xffff0000, v5
	v_and_b32_e32 v5, 0xffff0000, v2
	v_lshlrev_b32_e32 v96, 16, v2
	v_lshlrev_b32_e32 v144, 16, v6
	v_and_b32_e32 v145, 0xffff0000, v6
	v_lshlrev_b32_e32 v6, 16, v3
	v_and_b32_e32 v98, 0xffff0000, v3
	v_lshlrev_b32_e32 v2, 16, v7
	v_and_b32_e32 v3, 0xffff0000, v7
	v_mul_f32_e32 v7, 0xbfb8aa3b, v90
	v_mul_f32_e32 v90, 0xbfb8aa3b, v92
	v_mul_f32_e32 v4, 0xbfb8aa3b, v4
	v_mul_f32_e32 v92, 0xbfb8aa3b, v94
	v_mul_f32_e32 v5, 0xbfb8aa3b, v5
	v_mul_f32_e32 v94, 0xbfb8aa3b, v96
	v_mul_f32_e32 v6, 0xbfb8aa3b, v6
	v_mul_f32_e32 v96, 0xbfb8aa3b, v98
	v_exp_f32_e32 v7, v7
	v_exp_f32_e32 v90, v90
	v_exp_f32_e32 v4, v4
	v_exp_f32_e32 v92, v92
	v_exp_f32_e32 v5, v5
	v_exp_f32_e32 v94, v94
	v_exp_f32_e32 v6, v6
	v_exp_f32_e32 v96, v96
	v_add_f32_e32 v7, 1.0, v7
	v_add_f32_e32 v90, 1.0, v90
	v_add_f32_e32 v98, 1.0, v4
	v_add_f32_e32 v92, 1.0, v92
	v_add_f32_e32 v100, 1.0, v5
	v_add_f32_e32 v94, 1.0, v94
	v_add_f32_e32 v102, 1.0, v6
	v_add_f32_e32 v96, 1.0, v96
	v_rcp_f32_e32 v5, v7
	v_rcp_f32_e32 v4, v90
	v_rcp_f32_e32 v7, v98
	v_rcp_f32_e32 v6, v92
	v_rcp_f32_e32 v147, v100
	v_rcp_f32_e32 v146, v94
	v_rcp_f32_e32 v148, v102
	v_rcp_f32_e32 v149, v96
	v_pk_mul_f32 v[4:5], v[4:5], v[142:143]
	v_pk_mul_f32 v[6:7], v[6:7], v[0:1]
	v_pk_mul_f32 v[0:1], v[146:147], v[144:145]
	v_pk_mul_f32 v[2:3], v[148:149], v[2:3]
	s_mov_b64 exec, s[10:11]
	v_add_u32_e32 v108, 0x1c000, v86
	ds_write_b128 v108, v[4:7]
	ds_write_b128 v108, v[0:3] offset:16
	s_mov_b64 exec, -1
	s_mov_b64 s[10:11], 0
	s_branch .LBB0_220
